# RWKV-7 chunk-record builder step 3: all 48 LDS operand words of the four CxC products read up front into spare registers (one wait) instead of a read-wait per matrix-op pair
# baseline (speedup 1.0000x reference)
.LBB0_334:
	s_or_b64 exec, exec, s[2:3]
	v_and_b32_e32 v20, 15, v107
	v_and_b32_e32 v0, 63, v107
	v_mul_u32_u24_e32 v18, 0x44, v20
	v_lshrrev_b32_e32 v17, 4, v0
	v_lshlrev_b32_e32 v0, 2, v18
	s_add_i32 s2, s16, 0x2200
	v_add_u32_e32 v21, s16, v0
	v_lshlrev_b32_e32 v19, 2, v17
	s_cmp_lg_u32 s23, 0
	v_add_u32_e32 v6, v21, v19
	s_cselect_b64 s[14:15], -1, 0
	s_cmp_eq_u32 s23, 0
	v_add_u32_e32 v32, 0x3000, v6
	s_waitcnt lgkmcnt(0)
	s_barrier
	v_add_u32_e32 v35, 0x1000, v6
	ds_read2_b32 v[166:167], v32 offset0:192 offset1:196
	ds_read2_b32 v[168:169], v32 offset0:200 offset1:204
	ds_read2_b32 v[170:171], v32 offset0:208 offset1:212
	ds_read2_b32 v[172:173], v32 offset0:216 offset1:220
	ds_read2_b32 v[174:175], v32 offset0:224 offset1:228
	ds_read2_b32 v[176:177], v32 offset0:232 offset1:236
	ds_read2_b32 v[178:179], v32 offset0:240 offset1:244
	ds_read2_b32 v[180:181], v32 offset0:248 offset1:252
	s_cselect_b64 vcc, -1, 0
	s_and_b64 s[0:1], vcc, exec
	s_cselect_b32 s0, s2, s16
	v_add3_u32 v34, s0, v0, v19
	ds_read2_b32 v[222:223], v34 offset0:0 offset1:4
	ds_read2_b32 v[224:225], v34 offset0:8 offset1:12
	ds_read2_b32 v[226:227], v34 offset0:16 offset1:20
	ds_read2_b32 v[228:229], v34 offset0:24 offset1:28
	ds_read2_b32 v[230:231], v34 offset0:32 offset1:36
	ds_read2_b32 v[232:233], v34 offset0:40 offset1:44
	ds_read2_b32 v[234:235], v34 offset0:48 offset1:52
	ds_read2_b32 v[236:237], v34 offset0:56 offset1:60
	ds_read2_b32 v[182:183], v35 offset0:64 offset1:68
	ds_read2_b32 v[184:185], v35 offset0:72 offset1:76
	ds_read2_b32 v[186:187], v35 offset0:80 offset1:84
	ds_read2_b32 v[188:189], v35 offset0:88 offset1:92
	ds_read2_b32 v[190:191], v35 offset0:96 offset1:100
	ds_read2_b32 v[192:193], v35 offset0:104 offset1:108
	ds_read2_b32 v[238:239], v35 offset0:112 offset1:116
	ds_read2_b32 v[240:241], v35 offset0:120 offset1:124
	s_waitcnt lgkmcnt(0)
	v_mfma_f32_16x16x4_f32 v[0:3], v166, v222, 0
	v_add_u32_e32 v35, 0x1000, v6
	v_cmp_lt_u32_e64 s[2:3], v19, v20
	s_lshl_b32 s0, s23, 11
	s_add_i32 s0, s16, s0
	v_mfma_f32_16x16x4_f32 v[0:3], v167, v223, v[0:3]
	v_mfma_f32_16x16x4_f32 v[0:3], v168, v224, v[0:3]
	v_mfma_f32_16x16x4_f32 v[0:3], v169, v225, v[0:3]
	v_mfma_f32_16x16x4_f32 v[0:3], v170, v226, v[0:3]
	v_mfma_f32_16x16x4_f32 v[0:3], v171, v227, v[0:3]
	v_mfma_f32_16x16x4_f32 v[0:3], v172, v228, v[0:3]
	v_mfma_f32_16x16x4_f32 v[0:3], v173, v229, v[0:3]
	v_mfma_f32_16x16x4_f32 v[0:3], v174, v230, v[0:3]
	v_mfma_f32_16x16x4_f32 v[0:3], v175, v231, v[0:3]
	v_mfma_f32_16x16x4_f32 v[0:3], v176, v232, v[0:3]
	v_mfma_f32_16x16x4_f32 v[0:3], v177, v233, v[0:3]
	v_mfma_f32_16x16x4_f32 v[4:7], v182, v222, 0
	v_cndmask_b32_e64 v22, 0, 1, s[2:3]
	v_cmp_le_u32_e64 s[2:3], v19, v20
	v_mfma_f32_16x16x4_f32 v[0:3], v178, v234, v[0:3]
	v_mfma_f32_16x16x4_f32 v[0:3], v179, v235, v[0:3]
	v_mfma_f32_16x16x4_f32 v[4:7], v183, v223, v[4:7]
	v_cndmask_b32_e64 v23, 0, 1, s[2:3]
	v_mfma_f32_16x16x4_f32 v[4:7], v184, v224, v[4:7]
	v_mfma_f32_16x16x4_f32 v[4:7], v185, v225, v[4:7]
	v_mfma_f32_16x16x4_f32 v[4:7], v186, v226, v[4:7]
	v_cndmask_b32_e32 v26, v23, v22, vcc
	v_mfma_f32_16x16x4_f32 v[4:7], v187, v227, v[4:7]
	v_mfma_f32_16x16x4_f32 v[4:7], v188, v228, v[4:7]
	v_mfma_f32_16x16x4_f32 v[4:7], v189, v229, v[4:7]
	v_mfma_f32_16x16x4_f32 v[4:7], v190, v230, v[4:7]
	v_mfma_f32_16x16x4_f32 v[4:7], v191, v231, v[4:7]
	v_mfma_f32_16x16x4_f32 v[4:7], v192, v232, v[4:7]
	v_and_b32_e32 v14, 1, v26
	v_cmp_eq_u32_e64 s[2:3], 1, v14
	v_or_b32_e32 v14, 1, v19
	v_lshl_add_u32 v12, v20, 2, s0
	v_mfma_f32_16x16x4_f32 v[4:7], v193, v233, v[4:7]
	v_lshlrev_b32_e32 v15, 8, v17
	v_add_u32_e32 v26, v12, v15
	v_mfma_f32_16x16x4_f32 v[0:3], v180, v236, v[0:3]
	v_mfma_f32_16x16x4_f32 v[4:7], v238, v234, v[4:7]
	v_lshl_add_u32 v10, v14, 6, v12
	v_mfma_f32_16x16x4_f32 v[0:3], v181, v237, v[0:3]
	v_mfma_f32_16x16x4_f32 v[4:7], v239, v235, v[4:7]
	s_nop 8
	v_cndmask_b32_e64 v13, 0, v0, s[2:3]
	v_cndmask_b32_e32 v0, v19, v14, vcc
	v_cmp_gt_u32_e64 s[4:5], v20, v0
	v_or_b32_e32 v0, 2, v19
	v_cmp_lt_u32_e64 s[6:7], v0, v20
	v_cndmask_b32_e64 v27, 0, v1, s[4:5]
	s_nop 0
	v_cndmask_b32_e64 v1, 0, 1, s[6:7]
	v_cmp_le_u32_e64 s[6:7], v0, v20
	s_nop 0
	v_mfma_f32_16x16x4_f32 v[4:7], v240, v236, v[4:7]
	v_cndmask_b32_e64 v22, 0, 1, s[6:7]
	v_cndmask_b32_e32 v1, v22, v1, vcc
	v_lshl_add_u32 v22, v0, 6, v12
	v_or_b32_e32 v0, 3, v19
	v_and_b32_e32 v1, 1, v1
	v_cmp_lt_u32_e64 s[10:11], v0, v20
	v_cmp_eq_u32_e64 s[6:7], 1, v1
	v_lshl_add_u32 v12, v0, 6, v12
	v_cndmask_b32_e64 v1, 0, 1, s[10:11]
	v_cmp_le_u32_e64 s[10:11], v0, v20
	v_cndmask_b32_e64 v11, 0, v2, s[6:7]
	s_nop 0
	v_cndmask_b32_e64 v2, 0, 1, s[10:11]
	v_cndmask_b32_e32 v1, v2, v1, vcc
	v_and_b32_e32 v1, 1, v1
	v_cmp_eq_u32_e64 s[10:11], 1, v1
	s_nop 1
	v_cndmask_b32_e64 v8, 0, v3, s[10:11]
	v_mfma_f32_16x16x4_f32 v[0:3], v241, v237, v[4:7]
	s_nop 9
	v_cndmask_b32_e64 v0, 0, v0, s[2:3]
	ds_write2st64_b32 v26, v13, v0 offset0:68 offset1:72
	v_cndmask_b32_e64 v0, 0, v1, s[4:5]
	ds_write2st64_b32 v10, v27, v0 offset0:68 offset1:72
	v_cndmask_b32_e64 v0, 0, v2, s[6:7]
	ds_write2st64_b32 v22, v11, v0 offset0:68 offset1:72
	v_cndmask_b32_e64 v0, 0, v3, s[10:11]
	v_cmp_gt_u32_e64 s[2:3], 16, v16
	ds_write2st64_b32 v12, v8, v0 offset0:68 offset1:72
	s_waitcnt lgkmcnt(0)
	s_barrier
	s_and_saveexec_b64 s[4:5], s[2:3]
	s_cbranch_execz .LBB0_336
	s_add_i32 s0, s16, 0x4404
	v_mov_b32_e32 v1, s0
	ds_read2_b32 v[2:3], v1 offset1:1
	s_add_i32 s0, s16, 0x4448
	v_mov_b32_e32 v4, s0
	v_cmp_eq_u32_e64 s[2:3], 0, v16
	ds_read2_b64 v[4:7], v4 offset1:1
	s_add_i32 s0, s16, 0x440c
	v_cndmask_b32_e64 v0, 0, 1.0, s[2:3]
	v_cmp_eq_u32_e64 s[2:3], 1, v16
	v_mov_b32_e32 v22, s16
	s_nop 0
	v_cndmask_b32_e64 v1, 0, 1.0, s[2:3]
	v_cmp_eq_u32_e64 s[2:3], 2, v16
	s_waitcnt lgkmcnt(1)
	v_fmac_f32_e32 v1, v0, v2
	v_cndmask_b32_e64 v2, 0, 1.0, s[2:3]
	v_fmac_f32_e32 v2, v0, v3
	s_waitcnt lgkmcnt(0)
	v_fmac_f32_e32 v2, v1, v4
	v_mov_b32_e32 v4, s0
	ds_read2_b32 v[8:9], v4 offset1:1
	v_cmp_eq_u32_e64 s[2:3], 3, v16
	s_add_i32 s0, s16, 0x448c
	v_mov_b32_e32 v4, s0
	v_cndmask_b32_e64 v3, 0, 1.0, s[2:3]
	v_cmp_eq_u32_e64 s[2:3], 4, v16
	ds_read2_b32 v[10:11], v4 offset1:1
	ds_read_b32 v60, v22 offset:17468
	ds_read_b64 v[12:13], v22 offset:17528
	v_cndmask_b32_e64 v4, 0, 1.0, s[2:3]
	s_waitcnt lgkmcnt(3)
	v_fmac_f32_e32 v3, v0, v8
	v_fmac_f32_e32 v4, v0, v9
	s_add_i32 s0, s16, 0x4414
	v_fmac_f32_e32 v3, v1, v5
	v_fmac_f32_e32 v4, v1, v6
	v_mov_b32_e32 v6, s0
	s_waitcnt lgkmcnt(2)
	v_fmac_f32_e32 v3, v2, v10
	ds_read_b128 v[24:27], v22 offset:17616
	v_fmac_f32_e32 v4, v2, v11
	ds_read2_b32 v[10:11], v6 offset1:1
	v_cmp_eq_u32_e64 s[2:3], 5, v16
	s_add_i32 s0, s16, 0x4494
	v_mov_b32_e32 v6, s0
	v_cndmask_b32_e64 v5, 0, 1.0, s[2:3]
	s_add_i32 s0, s16, 0x4514
	ds_read_b128 v[28:31], v22 offset:17632
	ds_read2_b32 v[36:37], v6 offset1:1
	ds_read_b64 v[8:9], v22 offset:18296
	ds_read_b32 v61, v22 offset:18364
	s_waitcnt lgkmcnt(4)
	v_fmac_f32_e32 v5, v0, v10
	v_mov_b32_e32 v6, s0
	v_fmac_f32_e32 v5, v1, v7
	ds_read2_b32 v[6:7], v6 offset1:1
	s_add_i32 s0, s16, 0x4458
	v_mov_b32_e32 v10, s0
	ds_read2_b64 v[32:35], v10 offset1:1
	s_waitcnt lgkmcnt(4)
	v_fmac_f32_e32 v5, v2, v36
	v_fmac_f32_e32 v4, v3, v24
	v_fmac_f32_e32 v5, v3, v25
	v_cmp_eq_u32_e64 s[2:3], 6, v16
	s_waitcnt lgkmcnt(1)
	v_fmac_f32_e32 v5, v4, v6
	s_add_i32 s0, s16, 0x4558
	v_cndmask_b32_e64 v6, 0, 1.0, s[2:3]
	v_fmac_f32_e32 v6, v0, v11
	s_waitcnt lgkmcnt(0)
	v_fmac_f32_e32 v6, v1, v32
	v_mov_b32_e32 v10, s0
	s_add_i32 s0, s16, 0x441c
	v_fmac_f32_e32 v6, v2, v37
	ds_read2_b64 v[36:39], v10 offset1:1
	v_mov_b32_e32 v10, s0
	ds_read2_b32 v[10:11], v10 offset1:1
	v_fmac_f32_e32 v6, v3, v26
	v_cmp_eq_u32_e64 s[2:3], 7, v16
	v_fmac_f32_e32 v6, v4, v7
	s_add_i32 s0, s16, 0x449c
	v_cndmask_b32_e64 v7, 0, 1.0, s[2:3]
	s_waitcnt lgkmcnt(0)
	v_fmac_f32_e32 v7, v0, v10
	v_mov_b32_e32 v10, s0
	ds_read2_b32 v[24:25], v10 offset1:1
	s_add_i32 s0, s16, 0x451c
	v_mov_b32_e32 v10, s0
	s_add_i32 s0, s16, 0x459c
	v_mov_b32_e32 v23, s0
	s_add_i32 s0, s16, 0x4424
	v_fmac_f32_e32 v7, v1, v33
	v_mov_b32_e32 v26, s0
	ds_read2_b32 v[32:33], v10 offset1:1
	ds_read2_b32 v[44:45], v23 offset1:1
	ds_read2_b32 v[48:49], v26 offset1:1
	v_cmp_eq_u32_e64 s[2:3], 8, v16
	s_add_i32 s0, s16, 0x44a4
	s_waitcnt lgkmcnt(3)
	v_fmac_f32_e32 v7, v2, v24
	v_cndmask_b32_e64 v24, 0, 1.0, s[2:3]
	v_mov_b32_e32 v10, s0
	v_fmac_f32_e32 v24, v0, v11
	ds_read_b128 v[40:43], v22 offset:17888
	ds_read2_b32 v[10:11], v10 offset1:1
	v_fmac_f32_e32 v24, v1, v34
	v_cmp_eq_u32_e64 s[2:3], 9, v16
	s_add_i32 s0, s16, 0x4524
	v_fmac_f32_e32 v24, v2, v25
	v_cndmask_b32_e64 v25, 0, 1.0, s[2:3]
	v_mov_b32_e32 v23, s0
	s_add_i32 s0, s16, 0x45a4
	v_fmac_f32_e32 v7, v3, v27
	v_fmac_f32_e32 v24, v3, v28
	s_waitcnt lgkmcnt(2)
	v_fmac_f32_e32 v25, v0, v48
	v_mov_b32_e32 v28, s0
	s_add_i32 s0, s16, 0x4624
	v_fmac_f32_e32 v7, v4, v32
	v_fmac_f32_e32 v24, v4, v33
	v_fmac_f32_e32 v25, v1, v35
	v_mov_b32_e32 v32, s0
	s_add_i32 s0, s16, 0x4468
	v_fmac_f32_e32 v6, v5, v36
	v_fmac_f32_e32 v7, v5, v37
	v_fmac_f32_e32 v24, v5, v38
	s_waitcnt lgkmcnt(0)
	v_fmac_f32_e32 v25, v2, v10
	v_mov_b32_e32 v10, s0
	v_fmac_f32_e32 v7, v6, v44
	v_fmac_f32_e32 v24, v6, v45
	ds_read_b128 v[44:47], v22 offset:17904
	ds_read2_b32 v[26:27], v23 offset1:1
	ds_read2_b32 v[50:51], v28 offset1:1
	ds_read2_b32 v[52:53], v32 offset1:1
	ds_read2_b64 v[32:35], v10 offset1:1
	v_fmac_f32_e32 v25, v3, v29
	v_cmp_eq_u32_e64 s[2:3], 10, v16
	s_add_i32 s0, s16, 0x4568
	s_waitcnt lgkmcnt(3)
	v_fmac_f32_e32 v25, v4, v26
	v_cndmask_b32_e64 v26, 0, 1.0, s[2:3]
	v_mov_b32_e32 v10, s0
	v_fmac_f32_e32 v25, v5, v39
	v_fmac_f32_e32 v26, v0, v49
	ds_read2_b64 v[36:39], v10 offset1:1
	s_waitcnt lgkmcnt(1)
	v_fmac_f32_e32 v26, v1, v32
	v_fmac_f32_e32 v26, v2, v11
	v_fmac_f32_e32 v26, v3, v30
	v_fmac_f32_e32 v26, v4, v27
	s_add_i32 s0, s16, 0x4668
	s_waitcnt lgkmcnt(0)
	v_fmac_f32_e32 v26, v5, v36
	v_mov_b32_e32 v10, s0
	s_add_i32 s0, s16, 0x442c
	v_fmac_f32_e32 v25, v6, v50
	v_fmac_f32_e32 v26, v6, v51
	ds_read2_b64 v[48:51], v10 offset1:1
	v_mov_b32_e32 v10, s0
	ds_read2_b32 v[10:11], v10 offset1:1
	v_cmp_eq_u32_e64 s[2:3], 11, v16
	s_add_i32 s0, s16, 0x44ac
	v_fmac_f32_e32 v24, v7, v40
	v_cndmask_b32_e64 v27, 0, 1.0, s[2:3]
	s_waitcnt lgkmcnt(0)
	v_fmac_f32_e32 v27, v0, v10
	v_mov_b32_e32 v10, s0
	ds_read2_b32 v[28:29], v10 offset1:1
	s_add_i32 s0, s16, 0x452c
	v_mov_b32_e32 v10, s0
	s_add_i32 s0, s16, 0x45ac
	v_fmac_f32_e32 v25, v7, v41
	v_fmac_f32_e32 v26, v7, v42
	v_mov_b32_e32 v23, s0
	s_add_i32 s0, s16, 0x462c
	v_fmac_f32_e32 v25, v24, v52
	v_fmac_f32_e32 v26, v24, v53
	v_fmac_f32_e32 v27, v1, v33
	v_mov_b32_e32 v30, s0
	ds_read2_b32 v[40:41], v10 offset1:1
	ds_read2_b32 v[52:53], v23 offset1:1
	ds_read2_b32 v[54:55], v30 offset1:1
	s_waitcnt lgkmcnt(3)
	v_fmac_f32_e32 v27, v2, v28
	v_fmac_f32_e32 v27, v3, v31
	s_waitcnt lgkmcnt(2)
	v_fmac_f32_e32 v27, v4, v40
	s_add_i32 s0, s16, 0x46ac
	v_fmac_f32_e32 v27, v5, v37
	v_mov_b32_e32 v10, s0
	s_add_i32 s0, s16, 0x4434
	s_waitcnt lgkmcnt(1)
	v_fmac_f32_e32 v27, v6, v52
	ds_read2_b32 v[36:37], v10 offset1:1
	v_mov_b32_e32 v10, s0
	s_add_i32 s0, s16, 0x44b4
	v_fmac_f32_e32 v27, v7, v43
	v_mov_b32_e32 v23, s0
	s_add_i32 s0, s16, 0x4534
	s_waitcnt lgkmcnt(1)
	v_fmac_f32_e32 v27, v24, v54
	v_mov_b32_e32 v28, s0
	v_cmp_eq_u32_e64 s[2:3], 12, v16
	v_fmac_f32_e32 v26, v25, v48
	v_fmac_f32_e32 v27, v25, v49
	ds_read2_b32 v[48:49], v10 offset1:1
	ds_read2_b32 v[56:57], v23 offset1:1
	ds_read2_b32 v[58:59], v28 offset1:1
	v_cndmask_b32_e64 v28, 0, 1.0, s[2:3]
	v_fmac_f32_e32 v28, v0, v11
	ds_read_b128 v[30:33], v22 offset:17648
	ds_read_b64 v[10:11], v22 offset:17784
	v_fmac_f32_e32 v28, v1, v34
	v_cmp_eq_u32_e64 s[2:3], 13, v16
	v_fmac_f32_e32 v28, v2, v29
	s_add_i32 s0, s16, 0x45b4
	v_cndmask_b32_e64 v29, 0, 1.0, s[2:3]
	s_waitcnt lgkmcnt(4)
	v_fmac_f32_e32 v29, v0, v48
	v_fmac_f32_e32 v29, v1, v35
	s_waitcnt lgkmcnt(3)
	v_fmac_f32_e32 v29, v2, v56
	v_mov_b32_e32 v23, s0
	s_waitcnt lgkmcnt(1)
	v_fmac_f32_e32 v28, v3, v30
	v_fmac_f32_e32 v29, v3, v31
	ds_read2_b32 v[30:31], v23 offset1:1
	v_fmac_f32_e32 v29, v4, v58
	v_fmac_f32_e32 v28, v4, v41
	v_fmac_f32_e32 v29, v5, v39
	v_cmp_eq_u32_e64 s[2:3], 14, v16
	v_fmac_f32_e32 v28, v5, v38
	s_waitcnt lgkmcnt(0)
	v_fmac_f32_e32 v29, v6, v30
	v_cndmask_b32_e64 v30, 0, 1.0, s[2:3]
	v_fmac_f32_e32 v28, v6, v53
	ds_read_b128 v[40:43], v22 offset:18160
	v_fmac_f32_e32 v30, v0, v49
	v_fmac_f32_e32 v28, v7, v44
	v_fmac_f32_e32 v30, v1, v12
	v_fmac_f32_e32 v28, v24, v55
	s_add_i32 s0, s16, 0x4634
	v_fmac_f32_e32 v30, v2, v57
	v_fmac_f32_e32 v28, v25, v50
	v_mov_b32_e32 v23, s0
	s_add_i32 s0, s16, 0x46b4
	v_fmac_f32_e32 v30, v3, v32
	v_fmac_f32_e32 v27, v26, v36
	v_fmac_f32_e32 v28, v26, v37
	ds_read_b64 v[36:37], v22 offset:18040
	v_mov_b32_e32 v38, s0
	s_add_i32 s0, s16, 0x4734
	v_fmac_f32_e32 v30, v4, v59
	s_waitcnt lgkmcnt(1)
	v_fmac_f32_e32 v28, v27, v40
	v_mov_b32_e32 v40, s0
	ds_read2_b32 v[34:35], v23 offset1:1
	ds_read2_b32 v[38:39], v38 offset1:1
	ds_read2_b32 v[52:53], v40 offset1:1
	v_fmac_f32_e32 v30, v5, v10
	v_fmac_f32_e32 v30, v6, v31
	v_fmac_f32_e32 v29, v7, v45
	v_fmac_f32_e32 v30, v7, v46
	s_waitcnt lgkmcnt(2)
	v_fmac_f32_e32 v29, v24, v34
	v_fmac_f32_e32 v30, v24, v35
	v_fmac_f32_e32 v29, v25, v51
	v_fmac_f32_e32 v30, v25, v36
	s_waitcnt lgkmcnt(1)
	v_fmac_f32_e32 v29, v26, v38
	v_fmac_f32_e32 v30, v26, v39
	v_fmac_f32_e32 v29, v27, v41
	v_fmac_f32_e32 v30, v27, v42
	s_waitcnt lgkmcnt(0)
	v_fmac_f32_e32 v29, v28, v52
	v_fmac_f32_e32 v30, v28, v53
	v_fmac_f32_e32 v30, v29, v8
	v_add_u32_e32 v8, 0x4400, v22
	ds_read2_b32 v[22:23], v8 offset0:47 offset1:79
	v_cmp_eq_u32_e64 s[2:3], 15, v16
	s_nop 1
	v_cndmask_b32_e64 v31, 0, 1.0, s[2:3]
	v_fmac_f32_e32 v31, v0, v60
	v_fmac_f32_e32 v31, v1, v13
	ds_read2_b32 v[12:13], v8 offset0:111 offset1:143
	s_waitcnt lgkmcnt(1)
	v_fmac_f32_e32 v31, v2, v22
	v_fmac_f32_e32 v31, v3, v33
	v_fmac_f32_e32 v31, v4, v23
	v_fmac_f32_e32 v31, v5, v11
	ds_read2_b32 v[10:11], v8 offset0:175 offset1:207
	s_waitcnt lgkmcnt(1)
	v_fmac_f32_e32 v31, v6, v12
	v_fmac_f32_e32 v31, v7, v47
	v_fmac_f32_e32 v31, v24, v13
	v_fmac_f32_e32 v31, v25, v37
	s_waitcnt lgkmcnt(0)
	v_fmac_f32_e32 v31, v26, v10
	v_fmac_f32_e32 v31, v27, v43
	v_fmac_f32_e32 v31, v28, v11
	v_fmac_f32_e32 v31, v29, v9
	v_lshl_add_u32 v8, v16, 6, s16
	v_fmac_f32_e32 v31, v30, v61
	ds_write_b128 v8, v[0:3] offset:21504
	ds_write_b128 v8, v[4:7] offset:21520
	ds_write_b128 v8, v[24:27] offset:21536
	ds_write_b128 v8, v[28:31] offset:21552
